# v25: v23 + panel-switch row-scale table of kinds 1/6 filled inside the SwiGLU epilogue (loads issued at its start, table built half way) instead of a load round trip at the top of the last K iteration
# baseline (speedup 1.0000x reference)
_Z10fwd_kernel4Args:
	s_mov_b32 s100, 0
	s_load_dword s3, s[0:1], 0xa0
	s_add_u32 s26, s0, 0xa0
	s_addc_u32 s27, s1, 0
	v_readfirstlane_b32 s12, v0
	s_mov_b32 s13, s2
	s_waitcnt lgkmcnt(0)
	s_and_b32 s4, s3, 7
	s_cmp_lg_u32 s4, 0
	s_cbranch_scc1 .LBB0_2
	s_ashr_i32 s5, s2, 31
	s_lshr_b32 s5, s5, 29
	s_add_i32 s5, s2, s5
	s_ashr_i32 s6, s5, 3
	s_and_b32 s5, s5, -8
	s_ashr_i32 s4, s3, 3
	s_sub_i32 s5, s2, s5
	s_mul_i32 s4, s4, s5
	s_add_i32 s13, s4, s6

.LBB0_1189:
	v_writelane_b32 v255, s84, 40
	v_writelane_b32 v255, s85, 41
	v_writelane_b32 v255, s83, 42
	s_mov_b32 s100, 1
.LBB0_1191:
	s_mov_b32 s19, s82

.LBB0_1198:
	s_cmp_eq_u32 s100, 1
	s_cbranch_scc0 .Lfill3_noissue
	v_readlane_b32 s100, v255, 40
	v_readlane_b32 s101, v255, 41
	v_ashrrev_i32_e32 v172, 1, v0
	v_and_b32_e32 v173, 1, v0
	v_lshlrev_b32_e32 v174, 6, v172
	v_lshl_add_u32 v174, v173, 5, v174
	s_nop 1
	global_load_dwordx4 v[176:179], v174, s[100:101] sc1
	global_load_dwordx4 v[180:183], v174, s[100:101] offset:16 sc1
	s_nop 0
	s_mov_b32 s100, 2
.Lfill3_noissue:
	s_lshl_b32 s6, s45, 8
	s_and_b32 s6, s6, 0x400
	v_mov_b32_e32 v2, v150
	v_mov_b32_e32 v133, v149
	s_add_i32 s6, s55, s6
	v_pk_mul_f32 v[130:131], v[126:127], v[130:131]
	v_lshl_add_u32 v132, v133, 2, s6
	ds_read2_b32 v[154:155], v132 offset1:16
	v_add_u32_e32 v134, 0x800, v132
	ds_read2_b32 v[156:157], v134 offset1:16
	ds_read2_b32 v[144:145], v132 offset0:32 offset1:48
	ds_read2_b32 v[142:143], v134 offset0:32 offset1:48
	ds_read2_b32 v[140:141], v132 offset0:128 offset1:144
	ds_read2_b32 v[138:139], v134 offset0:128 offset1:144
	ds_read2_b32 v[136:137], v132 offset0:160 offset1:176
	ds_read2_b32 v[134:135], v134 offset0:160 offset1:176
	s_lshl_b32 s6, s68, 7
	s_mul_i32 s2, s45, 0x1a0000
	s_waitcnt lgkmcnt(7)
	v_pk_mul_f32 v[158:159], v[124:125], v[154:155] op_sel_hi:[1,0]
	v_pk_mul_f32 v[124:125], v[124:125], v[128:129]
	v_pk_mul_f32 v[128:129], v[116:117], v[154:155] op_sel_hi:[1,0]
	v_pk_mul_f32 v[116:117], v[116:117], v[120:121]
	v_exp_f32_e32 v128, v128
	v_exp_f32_e32 v129, v129
	v_exp_f32_e32 v158, v158
	v_exp_f32_e32 v159, v159
	v_pk_mul_f32 v[126:127], v[126:127], v[154:155] op_sel_hi:[1,0]
	s_waitcnt lgkmcnt(6)
	v_pk_fma_f32 v[128:129], v[156:157], v[128:129], v[156:157] op_sel_hi:[0,1,0]
	v_rcp_f32_e32 v128, v128
	v_rcp_f32_e32 v129, v129
	v_exp_f32_e32 v126, v126
	v_exp_f32_e32 v127, v127
	v_pk_fma_f32 v[158:159], v[156:157], v[158:159], v[156:157] op_sel_hi:[0,1,0]
	v_pk_mul_f32 v[120:121], v[116:117], v[128:129]
	v_pk_mul_f32 v[116:117], v[118:119], v[154:155] op_sel_hi:[1,0]
	v_rcp_f32_e32 v158, v158
	v_exp_f32_e32 v116, v116
	v_exp_f32_e32 v117, v117
	v_rcp_f32_e32 v159, v159
	v_pk_fma_f32 v[126:127], v[156:157], v[126:127], v[156:157] op_sel_hi:[0,1,0]
	v_rcp_f32_e32 v126, v126
	v_pk_fma_f32 v[116:117], v[156:157], v[116:117], v[156:157] op_sel_hi:[0,1,0]
	v_rcp_f32_e32 v127, v127
	v_rcp_f32_e32 v116, v116
	v_rcp_f32_e32 v117, v117
	s_or_b32 s6, s6, s44
	s_mul_hi_i32 s3, s45, 0x1a0000
	v_lshl_add_u32 v132, v2, 3, s6
	s_add_u32 s2, s98, s2
	s_addc_u32 s3, s99, s3
	v_add_u32_e32 v2, s61, v133
	v_mul_u32_u24_e32 v133, 0x1600, v2
	v_pk_mul_f32 v[124:125], v[124:125], v[158:159]
	v_pk_mul_f32 v[122:123], v[118:119], v[122:123]
	v_lshl_add_u32 v132, v132, 1, v133
	v_pk_mul_f32 v[126:127], v[130:131], v[126:127]
	v_pk_mul_f32 v[122:123], v[122:123], v[116:117]
	v_cvt_pk_bf16_f32 v116, v124, v125
	v_cvt_pk_bf16_f32 v117, v126, v127
	v_cvt_pk_bf16_f32 v118, v120, v121
	v_cvt_pk_bf16_f32 v119, v122, v123
	global_store_dwordx4 v132, v[116:119], s[2:3] sc1
	s_nop 1
	v_pk_mul_f32 v[120:121], v[108:109], v[154:155] op_sel:[0,1] op_sel_hi:[1,1]
	v_pk_mul_f32 v[108:109], v[108:109], v[112:113]
	v_pk_mul_f32 v[112:113], v[100:101], v[154:155] op_sel:[0,1] op_sel_hi:[1,1]
	v_exp_f32_e32 v112, v112
	v_exp_f32_e32 v113, v113
	v_pk_mul_f32 v[100:101], v[100:101], v[104:105]
	v_exp_f32_e32 v120, v120
	v_exp_f32_e32 v121, v121
	v_pk_fma_f32 v[112:113], v[156:157], v[112:113], v[156:157] op_sel:[1,0,1] op_sel_hi:[1,1,1]
	v_rcp_f32_e32 v112, v112
	v_rcp_f32_e32 v113, v113
	v_pk_mul_f32 v[114:115], v[110:111], v[114:115]
	v_pk_mul_f32 v[110:111], v[110:111], v[154:155] op_sel:[0,1] op_sel_hi:[1,1]
	v_pk_fma_f32 v[120:121], v[156:157], v[120:121], v[156:157] op_sel:[1,0,1] op_sel_hi:[1,1,1]
	v_pk_mul_f32 v[104:105], v[100:101], v[112:113]
	v_pk_mul_f32 v[100:101], v[102:103], v[154:155] op_sel:[0,1] op_sel_hi:[1,1]
	v_exp_f32_e32 v110, v110
	v_exp_f32_e32 v111, v111
	v_exp_f32_e32 v100, v100
	v_exp_f32_e32 v101, v101
	v_rcp_f32_e32 v120, v120
	v_rcp_f32_e32 v121, v121
	v_pk_fma_f32 v[110:111], v[156:157], v[110:111], v[156:157] op_sel:[1,0,1] op_sel_hi:[1,1,1]
	v_pk_fma_f32 v[100:101], v[156:157], v[100:101], v[156:157] op_sel:[1,0,1] op_sel_hi:[1,1,1]
	v_rcp_f32_e32 v110, v110
	v_rcp_f32_e32 v111, v111
	v_rcp_f32_e32 v100, v100
	v_rcp_f32_e32 v101, v101
	v_pk_mul_f32 v[108:109], v[108:109], v[120:121]
	v_pk_mul_f32 v[106:107], v[102:103], v[106:107]
	v_pk_mul_f32 v[110:111], v[114:115], v[110:111]
	v_pk_mul_f32 v[106:107], v[106:107], v[100:101]
	v_add_u32_e32 v112, 0x16000, v132
	v_cvt_pk_bf16_f32 v100, v108, v109
	v_cvt_pk_bf16_f32 v101, v110, v111
	v_cvt_pk_bf16_f32 v102, v104, v105
	v_cvt_pk_bf16_f32 v103, v106, v107
	global_store_dwordx4 v112, v[100:103], s[2:3] sc1
	s_nop 1
	s_waitcnt lgkmcnt(5)
	v_pk_mul_f32 v[102:103], v[92:93], v[144:145] op_sel_hi:[1,0]
	v_pk_mul_f32 v[92:93], v[92:93], v[96:97]
	v_pk_mul_f32 v[96:97], v[84:85], v[144:145] op_sel_hi:[1,0]
	v_pk_mul_f32 v[84:85], v[84:85], v[88:89]
	v_exp_f32_e32 v96, v96
	v_exp_f32_e32 v97, v97
	v_exp_f32_e32 v102, v102
	v_exp_f32_e32 v103, v103
	v_pk_mul_f32 v[98:99], v[94:95], v[98:99]
	s_waitcnt lgkmcnt(4)
	v_pk_fma_f32 v[96:97], v[142:143], v[96:97], v[142:143] op_sel_hi:[0,1,0]
	v_rcp_f32_e32 v96, v96
	v_rcp_f32_e32 v97, v97
	v_pk_mul_f32 v[94:95], v[94:95], v[144:145] op_sel_hi:[1,0]
	v_pk_fma_f32 v[102:103], v[142:143], v[102:103], v[142:143] op_sel_hi:[0,1,0]
	v_exp_f32_e32 v94, v94
	v_pk_mul_f32 v[88:89], v[84:85], v[96:97]
	v_pk_mul_f32 v[84:85], v[86:87], v[144:145] op_sel_hi:[1,0]
	v_exp_f32_e32 v95, v95
	v_exp_f32_e32 v84, v84
	v_exp_f32_e32 v85, v85
	v_rcp_f32_e32 v102, v102
	v_rcp_f32_e32 v103, v103
	v_pk_fma_f32 v[94:95], v[142:143], v[94:95], v[142:143] op_sel_hi:[0,1,0]
	v_pk_fma_f32 v[84:85], v[142:143], v[84:85], v[142:143] op_sel_hi:[0,1,0]
	v_rcp_f32_e32 v94, v94
	v_rcp_f32_e32 v95, v95
	v_rcp_f32_e32 v84, v84
	v_rcp_f32_e32 v85, v85
	v_pk_mul_f32 v[92:93], v[92:93], v[102:103]
	v_pk_mul_f32 v[90:91], v[86:87], v[90:91]
	v_pk_mul_f32 v[94:95], v[98:99], v[94:95]
	v_pk_mul_f32 v[90:91], v[90:91], v[84:85]
	v_add_u32_e32 v96, 0x2c000, v132
	v_cvt_pk_bf16_f32 v84, v92, v93
	v_cvt_pk_bf16_f32 v85, v94, v95
	v_cvt_pk_bf16_f32 v86, v88, v89
	v_cvt_pk_bf16_f32 v87, v90, v91
	global_store_dwordx4 v96, v[84:87], s[2:3] sc1
	s_nop 1
	v_pk_mul_f32 v[88:89], v[76:77], v[144:145] op_sel:[0,1] op_sel_hi:[1,1]
	v_pk_mul_f32 v[76:77], v[76:77], v[80:81]
	v_pk_mul_f32 v[80:81], v[64:65], v[144:145] op_sel:[0,1] op_sel_hi:[1,1]
	v_exp_f32_e32 v80, v80
	v_exp_f32_e32 v81, v81
	v_pk_mul_f32 v[82:83], v[78:79], v[82:83]
	v_pk_mul_f32 v[78:79], v[78:79], v[144:145] op_sel:[0,1] op_sel_hi:[1,1]
	v_pk_mul_f32 v[64:65], v[64:65], v[72:73]
	v_pk_fma_f32 v[80:81], v[142:143], v[80:81], v[142:143] op_sel:[1,0,1] op_sel_hi:[1,1,1]
	v_rcp_f32_e32 v80, v80
	v_rcp_f32_e32 v81, v81
	v_exp_f32_e32 v88, v88
	v_exp_f32_e32 v89, v89
	v_exp_f32_e32 v78, v78
	v_exp_f32_e32 v79, v79
	v_pk_mul_f32 v[72:73], v[64:65], v[80:81]
	v_pk_mul_f32 v[64:65], v[66:67], v[144:145] op_sel:[0,1] op_sel_hi:[1,1]
	v_pk_fma_f32 v[88:89], v[142:143], v[88:89], v[142:143] op_sel:[1,0,1] op_sel_hi:[1,1,1]
	v_exp_f32_e32 v64, v64
	v_exp_f32_e32 v65, v65
	v_pk_fma_f32 v[78:79], v[142:143], v[78:79], v[142:143] op_sel:[1,0,1] op_sel_hi:[1,1,1]
	v_rcp_f32_e32 v88, v88
	v_rcp_f32_e32 v89, v89
	v_rcp_f32_e32 v78, v78
	v_rcp_f32_e32 v79, v79
	v_pk_fma_f32 v[64:65], v[142:143], v[64:65], v[142:143] op_sel:[1,0,1] op_sel_hi:[1,1,1]
	v_rcp_f32_e32 v64, v64
	v_rcp_f32_e32 v65, v65
	v_pk_mul_f32 v[76:77], v[76:77], v[88:89]
	v_pk_mul_f32 v[78:79], v[82:83], v[78:79]
	v_pk_mul_f32 v[74:75], v[66:67], v[74:75]
	v_add_u32_e32 v80, 0x42000, v132
	v_pk_mul_f32 v[74:75], v[74:75], v[64:65]
	v_cvt_pk_bf16_f32 v64, v76, v77
	v_cvt_pk_bf16_f32 v65, v78, v79
	v_cvt_pk_bf16_f32 v66, v72, v73
	v_cvt_pk_bf16_f32 v67, v74, v75
	global_store_dwordx4 v80, v[64:67], s[2:3] sc1
	s_nop 1
	v_add_u32_e32 v65, 0xb0000, v132
	s_waitcnt lgkmcnt(3)
	v_pk_mul_f32 v[66:67], v[60:61], v[140:141] op_sel_hi:[1,0]
	v_pk_mul_f32 v[60:61], v[60:61], v[68:69]
	v_exp_f32_e32 v66, v66
	v_exp_f32_e32 v67, v67
	v_pk_mul_f32 v[70:71], v[62:63], v[70:71]
	v_pk_mul_f32 v[62:63], v[62:63], v[140:141] op_sel_hi:[1,0]
	v_pk_mul_f32 v[58:59], v[54:55], v[58:59]
	s_waitcnt lgkmcnt(2)
	v_pk_fma_f32 v[66:67], v[138:139], v[66:67], v[138:139] op_sel_hi:[0,1,0]
	v_rcp_f32_e32 v66, v66
	v_rcp_f32_e32 v67, v67
	v_exp_f32_e32 v62, v62
	v_exp_f32_e32 v63, v63
	v_pk_mul_f32 v[50:51], v[46:47], v[50:51]
	v_pk_mul_f32 v[60:61], v[60:61], v[66:67]
	v_pk_mul_f32 v[66:67], v[52:53], v[140:141] op_sel_hi:[1,0]
	v_pk_mul_f32 v[52:53], v[52:53], v[56:57]
	v_exp_f32_e32 v66, v66
	v_exp_f32_e32 v67, v67
	v_pk_fma_f32 v[62:63], v[138:139], v[62:63], v[138:139] op_sel_hi:[0,1,0]
	v_rcp_f32_e32 v62, v62
	v_rcp_f32_e32 v63, v63
	v_pk_fma_f32 v[66:67], v[138:139], v[66:67], v[138:139] op_sel_hi:[0,1,0]
	v_rcp_f32_e32 v66, v66
	v_rcp_f32_e32 v67, v67
	v_pk_mul_f32 v[62:63], v[70:71], v[62:63]
	v_pk_mul_f32 v[42:43], v[38:39], v[42:43]
	v_pk_mul_f32 v[34:35], v[30:31], v[34:35]
	v_pk_mul_f32 v[56:57], v[52:53], v[66:67]
	v_pk_mul_f32 v[52:53], v[54:55], v[140:141] op_sel_hi:[1,0]
	v_cvt_pk_bf16_f32 v54, v56, v57
	v_exp_f32_e32 v52, v52
	v_exp_f32_e32 v53, v53
	v_pk_mul_f32 v[26:27], v[22:23], v[26:27]
	v_pk_fma_f32 v[52:53], v[138:139], v[52:53], v[138:139] op_sel_hi:[0,1,0]
	v_rcp_f32_e32 v52, v52
	v_rcp_f32_e32 v53, v53
	v_pk_mul_f32 v[18:19], v[14:15], v[18:19]
	v_pk_mul_f32 v[10:11], v[6:7], v[10:11]
	s_cmp_eq_u32 s100, 2
	s_cbranch_scc0 .Lfill3_done
	s_waitcnt vmcnt(4)
	v_add_f32_e32 v176, v176, v177
	v_add_f32_e32 v178, v178, v179
	v_add_f32_e32 v176, v176, v178
	v_add_f32_e32 v180, v180, v181
	v_add_f32_e32 v182, v182, v183
	v_add_f32_e32 v180, v180, v182
	v_add_f32_e32 v176, v176, v180
	v_and_b32_e32 v177, 64, v192
	v_xor_b32_e32 v178, 1, v192
	v_add_u32_e32 v177, 64, v177
	v_cmp_lt_i32_e32 vcc, v178, v177
	s_nop 1
	v_cndmask_b32_e32 v178, v192, v178, vcc
	v_lshlrev_b32_e32 v178, 2, v178
	ds_bpermute_b32 v178, v178, v176
	v_readlane_b32 s101, v255, 42
	v_cmp_eq_u32_e32 vcc, 0, v173
	s_waitcnt lgkmcnt(0)
	v_add_f32_e32 v176, v176, v178
	v_fmamk_f32 v176, v176, 0x3a800000, v254
	v_rsq_f32_e32 v178, v176
	v_lshl_add_u32 v172, v172, 2, s101
	s_mov_b64 exec, vcc
	v_mul_f32_e32 v178, 0xbfb8aa3b, v178
	ds_write2st64_b32 v172, v178, v176 offset1:8
	s_mov_b64 exec, -1
	s_mov_b32 s100, 0
.Lfill3_done:
	s_cmp_eq_u32 s82, s45
	v_pk_mul_f32 v[58:59], v[58:59], v[52:53]
	v_cvt_pk_bf16_f32 v52, v60, v61
	v_cvt_pk_bf16_f32 v53, v62, v63
	v_cvt_pk_bf16_f32 v55, v58, v59
	global_store_dwordx4 v65, v[52:55], s[2:3] sc1
	s_nop 1
	v_pk_mul_f32 v[56:57], v[44:45], v[140:141] op_sel:[0,1] op_sel_hi:[1,1]
	v_pk_mul_f32 v[44:45], v[44:45], v[48:49]
	v_pk_mul_f32 v[48:49], v[36:37], v[140:141] op_sel:[0,1] op_sel_hi:[1,1]
	v_exp_f32_e32 v48, v48
	v_exp_f32_e32 v49, v49
	v_pk_mul_f32 v[36:37], v[36:37], v[40:41]
	v_exp_f32_e32 v56, v56
	v_exp_f32_e32 v57, v57
	v_pk_fma_f32 v[48:49], v[138:139], v[48:49], v[138:139] op_sel:[1,0,1] op_sel_hi:[1,1,1]
	v_rcp_f32_e32 v48, v48
	v_rcp_f32_e32 v49, v49
	v_pk_mul_f32 v[46:47], v[46:47], v[140:141] op_sel:[0,1] op_sel_hi:[1,1]
	v_pk_fma_f32 v[56:57], v[138:139], v[56:57], v[138:139] op_sel:[1,0,1] op_sel_hi:[1,1,1]
	v_exp_f32_e32 v46, v46
	v_pk_mul_f32 v[40:41], v[36:37], v[48:49]
	v_pk_mul_f32 v[36:37], v[38:39], v[140:141] op_sel:[0,1] op_sel_hi:[1,1]
	v_exp_f32_e32 v47, v47
	v_exp_f32_e32 v36, v36
	v_exp_f32_e32 v37, v37
	v_rcp_f32_e32 v56, v56
	v_rcp_f32_e32 v57, v57
	v_pk_fma_f32 v[46:47], v[138:139], v[46:47], v[138:139] op_sel:[1,0,1] op_sel_hi:[1,1,1]
	v_pk_fma_f32 v[36:37], v[138:139], v[36:37], v[138:139] op_sel:[1,0,1] op_sel_hi:[1,1,1]
	v_rcp_f32_e32 v46, v46
	v_rcp_f32_e32 v47, v47
	v_rcp_f32_e32 v36, v36
	v_rcp_f32_e32 v37, v37
	v_pk_mul_f32 v[44:45], v[44:45], v[56:57]
	v_pk_mul_f32 v[46:47], v[50:51], v[46:47]
	v_add_u32_e32 v48, 0xc6000, v132
	v_pk_mul_f32 v[42:43], v[42:43], v[36:37]
	v_cvt_pk_bf16_f32 v36, v44, v45
	v_cvt_pk_bf16_f32 v37, v46, v47
	v_cvt_pk_bf16_f32 v38, v40, v41
	v_cvt_pk_bf16_f32 v39, v42, v43
	global_store_dwordx4 v48, v[36:39], s[2:3] sc1
	s_nop 1
	s_waitcnt lgkmcnt(1)
	v_pk_mul_f32 v[38:39], v[28:29], v[136:137] op_sel_hi:[1,0]
	v_pk_mul_f32 v[28:29], v[28:29], v[32:33]
	v_pk_mul_f32 v[32:33], v[20:21], v[136:137] op_sel_hi:[1,0]
	v_pk_mul_f32 v[20:21], v[20:21], v[24:25]
	v_exp_f32_e32 v32, v32
	v_exp_f32_e32 v33, v33
	v_exp_f32_e32 v38, v38
	v_exp_f32_e32 v39, v39
	v_pk_mul_f32 v[30:31], v[30:31], v[136:137] op_sel_hi:[1,0]
	s_waitcnt lgkmcnt(0)
	v_pk_fma_f32 v[32:33], v[134:135], v[32:33], v[134:135] op_sel_hi:[0,1,0]
	v_rcp_f32_e32 v32, v32
	v_rcp_f32_e32 v33, v33
	v_exp_f32_e32 v30, v30
	v_exp_f32_e32 v31, v31
	v_pk_fma_f32 v[38:39], v[134:135], v[38:39], v[134:135] op_sel_hi:[0,1,0]
	v_pk_mul_f32 v[24:25], v[20:21], v[32:33]
	v_pk_mul_f32 v[20:21], v[22:23], v[136:137] op_sel_hi:[1,0]
	v_rcp_f32_e32 v38, v38
	v_exp_f32_e32 v20, v20
	v_exp_f32_e32 v21, v21
	v_rcp_f32_e32 v39, v39
	v_pk_fma_f32 v[30:31], v[134:135], v[30:31], v[134:135] op_sel_hi:[0,1,0]
	v_rcp_f32_e32 v30, v30
	v_pk_fma_f32 v[20:21], v[134:135], v[20:21], v[134:135] op_sel_hi:[0,1,0]
	v_rcp_f32_e32 v31, v31
	v_rcp_f32_e32 v20, v20
	v_rcp_f32_e32 v21, v21
	v_pk_mul_f32 v[28:29], v[28:29], v[38:39]
	v_pk_mul_f32 v[30:31], v[34:35], v[30:31]
	v_add_u32_e32 v32, 0xdc000, v132
	v_pk_mul_f32 v[26:27], v[26:27], v[20:21]
	v_cvt_pk_bf16_f32 v20, v28, v29
	v_cvt_pk_bf16_f32 v21, v30, v31
	v_cvt_pk_bf16_f32 v22, v24, v25
	v_cvt_pk_bf16_f32 v23, v26, v27
	global_store_dwordx4 v32, v[20:23], s[2:3] sc1
	s_nop 1
	v_pk_mul_f32 v[24:25], v[12:13], v[136:137] op_sel:[0,1] op_sel_hi:[1,1]
	v_pk_mul_f32 v[12:13], v[12:13], v[16:17]
	v_pk_mul_f32 v[16:17], v[4:5], v[136:137] op_sel:[0,1] op_sel_hi:[1,1]
	v_exp_f32_e32 v16, v16
	v_exp_f32_e32 v17, v17
	v_pk_mul_f32 v[4:5], v[4:5], v[8:9]
	v_pk_mul_f32 v[14:15], v[14:15], v[136:137] op_sel:[0,1] op_sel_hi:[1,1]
	v_exp_f32_e32 v24, v24
	v_pk_fma_f32 v[16:17], v[134:135], v[16:17], v[134:135] op_sel:[1,0,1] op_sel_hi:[1,1,1]
	v_rcp_f32_e32 v16, v16
	v_rcp_f32_e32 v17, v17
	v_exp_f32_e32 v25, v25
	v_exp_f32_e32 v14, v14
	v_exp_f32_e32 v15, v15
	v_pk_mul_f32 v[8:9], v[4:5], v[16:17]
	v_pk_mul_f32 v[4:5], v[6:7], v[136:137] op_sel:[0,1] op_sel_hi:[1,1]
	v_pk_fma_f32 v[24:25], v[134:135], v[24:25], v[134:135] op_sel:[1,0,1] op_sel_hi:[1,1,1]
	v_exp_f32_e32 v4, v4
	v_exp_f32_e32 v5, v5
	v_pk_fma_f32 v[14:15], v[134:135], v[14:15], v[134:135] op_sel:[1,0,1] op_sel_hi:[1,1,1]
	v_rcp_f32_e32 v24, v24
	v_rcp_f32_e32 v25, v25
	v_pk_fma_f32 v[4:5], v[134:135], v[4:5], v[134:135] op_sel:[1,0,1] op_sel_hi:[1,1,1]
	v_rcp_f32_e32 v14, v14
	v_rcp_f32_e32 v15, v15
	v_rcp_f32_e32 v4, v4
	v_rcp_f32_e32 v5, v5
	v_add_u32_e32 v2, 0xf2000, v132
	v_pk_mul_f32 v[12:13], v[12:13], v[24:25]
	v_pk_mul_f32 v[14:15], v[18:19], v[14:15]
	v_pk_mul_f32 v[10:11], v[10:11], v[4:5]
	v_cvt_pk_bf16_f32 v6, v8, v9
	v_cvt_pk_bf16_f32 v4, v12, v13
	v_cvt_pk_bf16_f32 v5, v14, v15
	v_cvt_pk_bf16_f32 v7, v10, v11
	global_store_dwordx4 v2, v[4:7], s[2:3] sc1
	s_nop 1
	s_cselect_b64 s[2:3], -1, 0
	s_and_b64 s[6:7], s[78:79], s[2:3]
	s_mov_b64 s[2:3], -1
	s_andn2_b64 vcc, exec, s[6:7]
	s_cbranch_vccz .LBB0_1206
	s_waitcnt vmcnt(0)
	s_mov_b64 s[2:3], exec
	v_readlane_b32 s6, v255, 11
	v_readlane_b32 s7, v255, 12
	s_and_b64 s[6:7], s[2:3], s[6:7]
	s_mov_b64 exec, s[6:7]
	s_cbranch_execz .LBB0_1201
	s_lshl_b32 s6, s45, 6
	s_add_i32 s6, s6, s15
	s_ashr_i32 s7, s6, 31
	s_add_i32 s12, s17, 1
	s_lshl_b64 s[6:7], s[6:7], 2
	v_readlane_b32 s13, v255, 5
	s_add_u32 s6, s13, s6
	v_readlane_b32 s13, v255, 6
	s_addc_u32 s7, s13, s7
	v_mov_b32_e32 v2, s12
	global_atomic_add v3, v2, s[6:7]
